# P11 pool pre-pass: history prologue (15 serialized load->wait round trips) and per-row old-row loads (8 per 8-row batch) batched: all loads issued up front, single wait, same math order
# speedup vs baseline: 1.0105x; 1.0026x over previous
; DI float bflo(unsigned w) { return __uint_as_float(w << 16); }
; DI float bfhi(unsigned w) { return __uint_as_float(w & 0xffff0000u); }
; __global__ void __launch_bounds__(512) fwd_kernel(Params P) {
;     ...
;                 for (int item = bx * 512 + tid; item < 131072; item += G * 512) {
;                     const int c0 = (item & 127) * 8, run = item >> 7, row0 = run * 32, t0 = row0 & (SEQ - 1), w = 2 << (c0 >> 8);
;                     float sum[8];
; #pragma unroll
;                     for (int e = 0; e < 8; ++e) sum[e] = 0.f;
;                     for (int i2 = 1; i2 < w; ++i2) if (t0 - i2 >= 0) { const u32x4 a = *(const u32x4*)(H16 + (size_t)(row0 - i2) * DM + c0); const float r = 1.f / sqrtf(SSQ[3 * (size_t)MT + row0 - i2] * (1.f / DM) + RMS_EPS);
; #pragma unroll
;                         for (int e = 0; e < 4; ++e) { sum[2 * e] += bflo(a[e]) * r; sum[2 * e + 1] += bfhi(a[e]) * r; } }
.LBB0_1279:
	v_ashrrev_i32_e32 v1, 2, v83
	v_and_b32_e32 v0, 0xffffffe0, v1
	v_bfe_u32 v2, v83, 5, 2
	v_and_b32_e32 v93, 0x3fe0, v1
	v_lshlrev_b32_e64 v95, v2, 2
	v_add_u32_e32 v2, 0x18000, v0
	v_ashrrev_i32_e32 v1, 31, v0
	v_lshlrev_b32_e32 v4, 1, v85
	v_ashrrev_i32_e32 v3, 31, v2
	v_lshlrev_b64 v[64:65], 11, v[0:1]
	v_and_or_b32 v64, v4, s22, v64
	v_lshlrev_b64 v[66:67], 2, v[2:3]
	v_lshl_add_u64 v[0:1], s[10:11], 0, v[64:65]
	v_lshl_add_u64 v[2:3], s[12:13], 0, v[66:67]
	s_mov_b64 s[4:5], exec
	v_mov_b32_e32 v80, 0
	v_mov_b32_e32 v81, v91
	v_mov_b32_e32 v78, 0
	v_mov_b32_e32 v79, v91
	v_mov_b32_e32 v76, 0
	v_mov_b32_e32 v77, v91
	v_mov_b32_e32 v74, 0
	v_mov_b32_e32 v75, v91
	v_cmp_ne_u32_e32 vcc, 0, v93
	s_and_b64 s[20:21], vcc, exec
	s_mov_b64 exec, s[20:21]
	s_cbranch_execz .Lp11_ld_done
	global_load_dword v96, v[2:3], off
	global_load_dwordx4 v[4:7], v[0:1], off
	v_lshl_add_u64 v[0:1], v[0:1], 0, s[16:17]
	v_lshl_add_u64 v[2:3], v[2:3], 0, -4
	v_cmp_lt_u32_e32 vcc, 2, v95
	s_and_b64 exec, vcc, s[20:21]
	s_cbranch_execz .Lp11_ld_done
	global_load_dword v97, v[2:3], off
	global_load_dwordx4 v[8:11], v[0:1], off
	v_lshl_add_u64 v[0:1], v[0:1], 0, s[16:17]
	v_lshl_add_u64 v[2:3], v[2:3], 0, -4
	v_cmp_lt_u32_e32 vcc, 3, v95
	s_and_b64 exec, vcc, s[20:21]
	s_cbranch_execz .Lp11_ld_done
	global_load_dword v98, v[2:3], off
	global_load_dwordx4 v[12:15], v[0:1], off
	v_lshl_add_u64 v[0:1], v[0:1], 0, s[16:17]
	v_lshl_add_u64 v[2:3], v[2:3], 0, -4
	v_cmp_lt_u32_e32 vcc, 4, v95
	s_and_b64 exec, vcc, s[20:21]
	s_cbranch_execz .Lp11_ld_done
	global_load_dword v99, v[2:3], off
	global_load_dwordx4 v[16:19], v[0:1], off
	v_lshl_add_u64 v[0:1], v[0:1], 0, s[16:17]
	v_lshl_add_u64 v[2:3], v[2:3], 0, -4
	v_cmp_lt_u32_e32 vcc, 5, v95
	s_and_b64 exec, vcc, s[20:21]
	s_cbranch_execz .Lp11_ld_done
	global_load_dword v100, v[2:3], off
	global_load_dwordx4 v[20:23], v[0:1], off
	v_lshl_add_u64 v[0:1], v[0:1], 0, s[16:17]
	v_lshl_add_u64 v[2:3], v[2:3], 0, -4
	v_cmp_lt_u32_e32 vcc, 6, v95
	s_and_b64 exec, vcc, s[20:21]
	s_cbranch_execz .Lp11_ld_done
	global_load_dword v101, v[2:3], off
	global_load_dwordx4 v[24:27], v[0:1], off
	v_lshl_add_u64 v[0:1], v[0:1], 0, s[16:17]
	v_lshl_add_u64 v[2:3], v[2:3], 0, -4
	v_cmp_lt_u32_e32 vcc, 7, v95
	s_and_b64 exec, vcc, s[20:21]
	s_cbranch_execz .Lp11_ld_done
	global_load_dword v102, v[2:3], off
	global_load_dwordx4 v[28:31], v[0:1], off
	v_lshl_add_u64 v[0:1], v[0:1], 0, s[16:17]
	v_lshl_add_u64 v[2:3], v[2:3], 0, -4
	v_cmp_lt_u32_e32 vcc, 8, v95
	s_and_b64 exec, vcc, s[20:21]
	s_cbranch_execz .Lp11_ld_done
	global_load_dword v103, v[2:3], off
	global_load_dwordx4 v[32:35], v[0:1], off
	v_lshl_add_u64 v[0:1], v[0:1], 0, s[16:17]
	v_lshl_add_u64 v[2:3], v[2:3], 0, -4
	v_cmp_lt_u32_e32 vcc, 9, v95
	s_and_b64 exec, vcc, s[20:21]
	s_cbranch_execz .Lp11_ld_done
	global_load_dword v104, v[2:3], off
	global_load_dwordx4 v[36:39], v[0:1], off
	v_lshl_add_u64 v[0:1], v[0:1], 0, s[16:17]
	v_lshl_add_u64 v[2:3], v[2:3], 0, -4
	v_cmp_lt_u32_e32 vcc, 10, v95
	s_and_b64 exec, vcc, s[20:21]
	s_cbranch_execz .Lp11_ld_done
	global_load_dword v105, v[2:3], off
	global_load_dwordx4 v[40:43], v[0:1], off
	v_lshl_add_u64 v[0:1], v[0:1], 0, s[16:17]
	v_lshl_add_u64 v[2:3], v[2:3], 0, -4
	v_cmp_lt_u32_e32 vcc, 11, v95
	s_and_b64 exec, vcc, s[20:21]
	s_cbranch_execz .Lp11_ld_done
	global_load_dword v106, v[2:3], off
	global_load_dwordx4 v[44:47], v[0:1], off
	v_lshl_add_u64 v[0:1], v[0:1], 0, s[16:17]
	v_lshl_add_u64 v[2:3], v[2:3], 0, -4
	v_cmp_lt_u32_e32 vcc, 12, v95
	s_and_b64 exec, vcc, s[20:21]
	s_cbranch_execz .Lp11_ld_done
	global_load_dword v107, v[2:3], off
	global_load_dwordx4 v[48:51], v[0:1], off
	v_lshl_add_u64 v[0:1], v[0:1], 0, s[16:17]
	v_lshl_add_u64 v[2:3], v[2:3], 0, -4
	v_cmp_lt_u32_e32 vcc, 13, v95
	s_and_b64 exec, vcc, s[20:21]
	s_cbranch_execz .Lp11_ld_done
	global_load_dword v108, v[2:3], off
	global_load_dwordx4 v[52:55], v[0:1], off
	v_lshl_add_u64 v[0:1], v[0:1], 0, s[16:17]
	v_lshl_add_u64 v[2:3], v[2:3], 0, -4
	v_cmp_lt_u32_e32 vcc, 14, v95
	s_and_b64 exec, vcc, s[20:21]
	s_cbranch_execz .Lp11_ld_done
	global_load_dword v109, v[2:3], off
	global_load_dwordx4 v[56:59], v[0:1], off
	v_lshl_add_u64 v[0:1], v[0:1], 0, s[16:17]
	v_lshl_add_u64 v[2:3], v[2:3], 0, -4
	v_cmp_lt_u32_e32 vcc, 15, v95
	s_and_b64 exec, vcc, s[20:21]
	s_cbranch_execz .Lp11_ld_done
	global_load_dword v110, v[2:3], off
	global_load_dwordx4 v[60:63], v[0:1], off
; DI float bflo(unsigned w) { return __uint_as_float(w << 16); }
; DI float bfhi(unsigned w) { return __uint_as_float(w & 0xffff0000u); }
; __global__ void __launch_bounds__(512) fwd_kernel(Params P) {
;     ...
;                     for (int i2 = 1; i2 < w; ++i2) if (t0 - i2 >= 0) { const u32x4 a = *(const u32x4*)(H16 + (size_t)(row0 - i2) * DM + c0); const float r = 1.f / sqrtf(SSQ[3 * (size_t)MT + row0 - i2] * (1.f / DM) + RMS_EPS);
; #pragma unroll
;                         for (int e = 0; e < 4; ++e) { sum[2 * e] += bflo(a[e]) * r; sum[2 * e + 1] += bfhi(a[e]) * r; } }
.Lp11_ld_done:
	s_waitcnt vmcnt(0)
	s_mov_b64 exec, s[20:21]
	s_cbranch_execz .Lp11_m_done
	v_fmamk_f32 v112, v96, 0x3a800000, v87
	v_mul_f32_e32 v113, 0x4f800000, v112
	v_cmp_gt_f32_e32 vcc, s23, v112
	v_lshlrev_b32_e32 v120, 16, v4
	v_and_b32_e32 v121, 0xffff0000, v4
	v_cndmask_b32_e32 v114, v112, v113, vcc
	v_sqrt_f32_e32 v115, v114
	v_lshlrev_b32_e32 v4, 16, v5
	v_and_b32_e32 v5, 0xffff0000, v5
	v_lshlrev_b32_e32 v112, 16, v6
	v_add_u32_e32 v116, -1, v115
	v_add_u32_e32 v117, 1, v115
	v_fma_f32 v118, -v116, v115, v114
	v_fma_f32 v119, -v117, v115, v114
	v_cmp_ge_f32_e64 s[0:1], 0, v118
	v_and_b32_e32 v113, 0xffff0000, v6
	v_lshlrev_b32_e32 v6, 16, v7
	v_cndmask_b32_e64 v115, v115, v116, s[0:1]
	v_cmp_lt_f32_e64 s[0:1], 0, v119
	v_and_b32_e32 v7, 0xffff0000, v7
	s_nop 0
	v_cndmask_b32_e64 v115, v115, v117, s[0:1]
	v_mul_f32_e32 v116, 0x37800000, v115
	v_cndmask_b32_e32 v115, v115, v116, vcc
	v_cmp_class_f32_e32 vcc, v114, v89
	s_nop 1
	v_cndmask_b32_e32 v114, v115, v114, vcc
	v_div_scale_f32 v115, s[0:1], v114, v114, 1.0
	v_rcp_f32_e32 v116, v115
	v_div_scale_f32 v117, vcc, 1.0, v114, 1.0
	v_fma_f32 v118, -v115, v116, 1.0
	v_fmac_f32_e32 v116, v118, v116
	v_mul_f32_e32 v118, v117, v116
	v_fma_f32 v119, -v115, v118, v117
	v_fmac_f32_e32 v118, v119, v116
	v_fma_f32 v115, -v115, v118, v117
	v_div_fmas_f32 v115, v115, v116, v118
	v_div_fixup_f32 v114, v115, v114, 1.0
	v_pk_fma_f32 v[80:81], v[114:115], v[120:121], v[80:81] op_sel_hi:[0,1,1]
	v_pk_fma_f32 v[78:79], v[114:115], v[4:5], v[78:79] op_sel_hi:[0,1,1]
	v_pk_fma_f32 v[76:77], v[114:115], v[112:113], v[76:77] op_sel_hi:[0,1,1]
	v_pk_fma_f32 v[74:75], v[114:115], v[6:7], v[74:75] op_sel_hi:[0,1,1]
	v_cmp_lt_u32_e32 vcc, 2, v95
	s_and_b64 exec, vcc, s[20:21]
	s_cbranch_execz .Lp11_m_done
	v_fmamk_f32 v112, v97, 0x3a800000, v87
	v_mul_f32_e32 v113, 0x4f800000, v112
	v_cmp_gt_f32_e32 vcc, s23, v112
	v_lshlrev_b32_e32 v120, 16, v8
	v_and_b32_e32 v121, 0xffff0000, v8
	v_cndmask_b32_e32 v114, v112, v113, vcc
	v_sqrt_f32_e32 v115, v114
	v_lshlrev_b32_e32 v8, 16, v9
	v_and_b32_e32 v9, 0xffff0000, v9
	v_lshlrev_b32_e32 v112, 16, v10
	v_add_u32_e32 v116, -1, v115
	v_add_u32_e32 v117, 1, v115
	v_fma_f32 v118, -v116, v115, v114
	v_fma_f32 v119, -v117, v115, v114
	v_cmp_ge_f32_e64 s[0:1], 0, v118
	v_and_b32_e32 v113, 0xffff0000, v10
	v_lshlrev_b32_e32 v10, 16, v11
	v_cndmask_b32_e64 v115, v115, v116, s[0:1]
	v_cmp_lt_f32_e64 s[0:1], 0, v119
	v_and_b32_e32 v11, 0xffff0000, v11
	s_nop 0
	v_cndmask_b32_e64 v115, v115, v117, s[0:1]
	v_mul_f32_e32 v116, 0x37800000, v115
	v_cndmask_b32_e32 v115, v115, v116, vcc
	v_cmp_class_f32_e32 vcc, v114, v89
	s_nop 1
	v_cndmask_b32_e32 v114, v115, v114, vcc
	v_div_scale_f32 v115, s[0:1], v114, v114, 1.0
	v_rcp_f32_e32 v116, v115
	v_div_scale_f32 v117, vcc, 1.0, v114, 1.0
	v_fma_f32 v118, -v115, v116, 1.0
	v_fmac_f32_e32 v116, v118, v116
	v_mul_f32_e32 v118, v117, v116
	v_fma_f32 v119, -v115, v118, v117
	v_fmac_f32_e32 v118, v119, v116
	v_fma_f32 v115, -v115, v118, v117
	v_div_fmas_f32 v115, v115, v116, v118
	v_div_fixup_f32 v114, v115, v114, 1.0
	v_pk_fma_f32 v[80:81], v[114:115], v[120:121], v[80:81] op_sel_hi:[0,1,1]
	v_pk_fma_f32 v[78:79], v[114:115], v[8:9], v[78:79] op_sel_hi:[0,1,1]
	v_pk_fma_f32 v[76:77], v[114:115], v[112:113], v[76:77] op_sel_hi:[0,1,1]
	v_pk_fma_f32 v[74:75], v[114:115], v[10:11], v[74:75] op_sel_hi:[0,1,1]
	v_cmp_lt_u32_e32 vcc, 3, v95
	s_and_b64 exec, vcc, s[20:21]
	s_cbranch_execz .Lp11_m_done
	v_fmamk_f32 v112, v98, 0x3a800000, v87
	v_mul_f32_e32 v113, 0x4f800000, v112
	v_cmp_gt_f32_e32 vcc, s23, v112
	v_lshlrev_b32_e32 v120, 16, v12
	v_and_b32_e32 v121, 0xffff0000, v12
	v_cndmask_b32_e32 v114, v112, v113, vcc
	v_sqrt_f32_e32 v115, v114
	v_lshlrev_b32_e32 v12, 16, v13
	v_and_b32_e32 v13, 0xffff0000, v13
	v_lshlrev_b32_e32 v112, 16, v14
	v_add_u32_e32 v116, -1, v115
	v_add_u32_e32 v117, 1, v115
	v_fma_f32 v118, -v116, v115, v114
	v_fma_f32 v119, -v117, v115, v114
	v_cmp_ge_f32_e64 s[0:1], 0, v118
	v_and_b32_e32 v113, 0xffff0000, v14
	v_lshlrev_b32_e32 v14, 16, v15
	v_cndmask_b32_e64 v115, v115, v116, s[0:1]
	v_cmp_lt_f32_e64 s[0:1], 0, v119
	v_and_b32_e32 v15, 0xffff0000, v15
	s_nop 0
	v_cndmask_b32_e64 v115, v115, v117, s[0:1]
	v_mul_f32_e32 v116, 0x37800000, v115
	v_cndmask_b32_e32 v115, v115, v116, vcc
	v_cmp_class_f32_e32 vcc, v114, v89
	s_nop 1
	v_cndmask_b32_e32 v114, v115, v114, vcc
	v_div_scale_f32 v115, s[0:1], v114, v114, 1.0
	v_rcp_f32_e32 v116, v115
	v_div_scale_f32 v117, vcc, 1.0, v114, 1.0
	v_fma_f32 v118, -v115, v116, 1.0
	v_fmac_f32_e32 v116, v118, v116
	v_mul_f32_e32 v118, v117, v116
	v_fma_f32 v119, -v115, v118, v117
	v_fmac_f32_e32 v118, v119, v116
	v_fma_f32 v115, -v115, v118, v117
	v_div_fmas_f32 v115, v115, v116, v118
	v_div_fixup_f32 v114, v115, v114, 1.0
	v_pk_fma_f32 v[80:81], v[114:115], v[120:121], v[80:81] op_sel_hi:[0,1,1]
	v_pk_fma_f32 v[78:79], v[114:115], v[12:13], v[78:79] op_sel_hi:[0,1,1]
	v_pk_fma_f32 v[76:77], v[114:115], v[112:113], v[76:77] op_sel_hi:[0,1,1]
	v_pk_fma_f32 v[74:75], v[114:115], v[14:15], v[74:75] op_sel_hi:[0,1,1]
	v_cmp_lt_u32_e32 vcc, 4, v95
	s_and_b64 exec, vcc, s[20:21]
	s_cbranch_execz .Lp11_m_done
; DI float bflo(unsigned w) { return __uint_as_float(w << 16); }
; DI float bfhi(unsigned w) { return __uint_as_float(w & 0xffff0000u); }
; __global__ void __launch_bounds__(512) fwd_kernel(Params P) {
;     ...
;                     for (int i2 = 1; i2 < w; ++i2) if (t0 - i2 >= 0) { const u32x4 a = *(const u32x4*)(H16 + (size_t)(row0 - i2) * DM + c0); const float r = 1.f / sqrtf(SSQ[3 * (size_t)MT + row0 - i2] * (1.f / DM) + RMS_EPS);
; #pragma unroll
;                         for (int e = 0; e < 4; ++e) { sum[2 * e] += bflo(a[e]) * r; sum[2 * e + 1] += bfhi(a[e]) * r; } }
	v_fmamk_f32 v112, v99, 0x3a800000, v87
	v_mul_f32_e32 v113, 0x4f800000, v112
	v_cmp_gt_f32_e32 vcc, s23, v112
	v_lshlrev_b32_e32 v120, 16, v16
	v_and_b32_e32 v121, 0xffff0000, v16
	v_cndmask_b32_e32 v114, v112, v113, vcc
	v_sqrt_f32_e32 v115, v114
	v_lshlrev_b32_e32 v16, 16, v17
	v_and_b32_e32 v17, 0xffff0000, v17
	v_lshlrev_b32_e32 v112, 16, v18
	v_add_u32_e32 v116, -1, v115
	v_add_u32_e32 v117, 1, v115
	v_fma_f32 v118, -v116, v115, v114
	v_fma_f32 v119, -v117, v115, v114
	v_cmp_ge_f32_e64 s[0:1], 0, v118
	v_and_b32_e32 v113, 0xffff0000, v18
	v_lshlrev_b32_e32 v18, 16, v19
	v_cndmask_b32_e64 v115, v115, v116, s[0:1]
	v_cmp_lt_f32_e64 s[0:1], 0, v119
	v_and_b32_e32 v19, 0xffff0000, v19
	s_nop 0
	v_cndmask_b32_e64 v115, v115, v117, s[0:1]
	v_mul_f32_e32 v116, 0x37800000, v115
	v_cndmask_b32_e32 v115, v115, v116, vcc
	v_cmp_class_f32_e32 vcc, v114, v89
	s_nop 1
	v_cndmask_b32_e32 v114, v115, v114, vcc
	v_div_scale_f32 v115, s[0:1], v114, v114, 1.0
	v_rcp_f32_e32 v116, v115
	v_div_scale_f32 v117, vcc, 1.0, v114, 1.0
	v_fma_f32 v118, -v115, v116, 1.0
	v_fmac_f32_e32 v116, v118, v116
	v_mul_f32_e32 v118, v117, v116
	v_fma_f32 v119, -v115, v118, v117
	v_fmac_f32_e32 v118, v119, v116
	v_fma_f32 v115, -v115, v118, v117
	v_div_fmas_f32 v115, v115, v116, v118
	v_div_fixup_f32 v114, v115, v114, 1.0
	v_pk_fma_f32 v[80:81], v[114:115], v[120:121], v[80:81] op_sel_hi:[0,1,1]
	v_pk_fma_f32 v[78:79], v[114:115], v[16:17], v[78:79] op_sel_hi:[0,1,1]
	v_pk_fma_f32 v[76:77], v[114:115], v[112:113], v[76:77] op_sel_hi:[0,1,1]
	v_pk_fma_f32 v[74:75], v[114:115], v[18:19], v[74:75] op_sel_hi:[0,1,1]
	v_cmp_lt_u32_e32 vcc, 5, v95
	s_and_b64 exec, vcc, s[20:21]
	s_cbranch_execz .Lp11_m_done
	v_fmamk_f32 v112, v100, 0x3a800000, v87
	v_mul_f32_e32 v113, 0x4f800000, v112
	v_cmp_gt_f32_e32 vcc, s23, v112
	v_lshlrev_b32_e32 v120, 16, v20
	v_and_b32_e32 v121, 0xffff0000, v20
	v_cndmask_b32_e32 v114, v112, v113, vcc
	v_sqrt_f32_e32 v115, v114
	v_lshlrev_b32_e32 v20, 16, v21
	v_and_b32_e32 v21, 0xffff0000, v21
	v_lshlrev_b32_e32 v112, 16, v22
	v_add_u32_e32 v116, -1, v115
	v_add_u32_e32 v117, 1, v115
	v_fma_f32 v118, -v116, v115, v114
	v_fma_f32 v119, -v117, v115, v114
	v_cmp_ge_f32_e64 s[0:1], 0, v118
	v_and_b32_e32 v113, 0xffff0000, v22
	v_lshlrev_b32_e32 v22, 16, v23
	v_cndmask_b32_e64 v115, v115, v116, s[0:1]
	v_cmp_lt_f32_e64 s[0:1], 0, v119
	v_and_b32_e32 v23, 0xffff0000, v23
	s_nop 0
	v_cndmask_b32_e64 v115, v115, v117, s[0:1]
	v_mul_f32_e32 v116, 0x37800000, v115
	v_cndmask_b32_e32 v115, v115, v116, vcc
	v_cmp_class_f32_e32 vcc, v114, v89
	s_nop 1
	v_cndmask_b32_e32 v114, v115, v114, vcc
	v_div_scale_f32 v115, s[0:1], v114, v114, 1.0
	v_rcp_f32_e32 v116, v115
	v_div_scale_f32 v117, vcc, 1.0, v114, 1.0
	v_fma_f32 v118, -v115, v116, 1.0
	v_fmac_f32_e32 v116, v118, v116
	v_mul_f32_e32 v118, v117, v116
	v_fma_f32 v119, -v115, v118, v117
	v_fmac_f32_e32 v118, v119, v116
	v_fma_f32 v115, -v115, v118, v117
	v_div_fmas_f32 v115, v115, v116, v118
	v_div_fixup_f32 v114, v115, v114, 1.0
	v_pk_fma_f32 v[80:81], v[114:115], v[120:121], v[80:81] op_sel_hi:[0,1,1]
	v_pk_fma_f32 v[78:79], v[114:115], v[20:21], v[78:79] op_sel_hi:[0,1,1]
	v_pk_fma_f32 v[76:77], v[114:115], v[112:113], v[76:77] op_sel_hi:[0,1,1]
	v_pk_fma_f32 v[74:75], v[114:115], v[22:23], v[74:75] op_sel_hi:[0,1,1]
	v_cmp_lt_u32_e32 vcc, 6, v95
	s_and_b64 exec, vcc, s[20:21]
	s_cbranch_execz .Lp11_m_done
	v_fmamk_f32 v112, v101, 0x3a800000, v87
	v_mul_f32_e32 v113, 0x4f800000, v112
	v_cmp_gt_f32_e32 vcc, s23, v112
	v_lshlrev_b32_e32 v120, 16, v24
	v_and_b32_e32 v121, 0xffff0000, v24
	v_cndmask_b32_e32 v114, v112, v113, vcc
	v_sqrt_f32_e32 v115, v114
	v_lshlrev_b32_e32 v24, 16, v25
	v_and_b32_e32 v25, 0xffff0000, v25
	v_lshlrev_b32_e32 v112, 16, v26
	v_add_u32_e32 v116, -1, v115
	v_add_u32_e32 v117, 1, v115
	v_fma_f32 v118, -v116, v115, v114
	v_fma_f32 v119, -v117, v115, v114
	v_cmp_ge_f32_e64 s[0:1], 0, v118
	v_and_b32_e32 v113, 0xffff0000, v26
	v_lshlrev_b32_e32 v26, 16, v27
	v_cndmask_b32_e64 v115, v115, v116, s[0:1]
	v_cmp_lt_f32_e64 s[0:1], 0, v119
	v_and_b32_e32 v27, 0xffff0000, v27
	s_nop 0
	v_cndmask_b32_e64 v115, v115, v117, s[0:1]
	v_mul_f32_e32 v116, 0x37800000, v115
	v_cndmask_b32_e32 v115, v115, v116, vcc
	v_cmp_class_f32_e32 vcc, v114, v89
	s_nop 1
	v_cndmask_b32_e32 v114, v115, v114, vcc
	v_div_scale_f32 v115, s[0:1], v114, v114, 1.0
	v_rcp_f32_e32 v116, v115
	v_div_scale_f32 v117, vcc, 1.0, v114, 1.0
	v_fma_f32 v118, -v115, v116, 1.0
	v_fmac_f32_e32 v116, v118, v116
	v_mul_f32_e32 v118, v117, v116
	v_fma_f32 v119, -v115, v118, v117
	v_fmac_f32_e32 v118, v119, v116
	v_fma_f32 v115, -v115, v118, v117
	v_div_fmas_f32 v115, v115, v116, v118
	v_div_fixup_f32 v114, v115, v114, 1.0
	v_pk_fma_f32 v[80:81], v[114:115], v[120:121], v[80:81] op_sel_hi:[0,1,1]
	v_pk_fma_f32 v[78:79], v[114:115], v[24:25], v[78:79] op_sel_hi:[0,1,1]
	v_pk_fma_f32 v[76:77], v[114:115], v[112:113], v[76:77] op_sel_hi:[0,1,1]
	v_pk_fma_f32 v[74:75], v[114:115], v[26:27], v[74:75] op_sel_hi:[0,1,1]
	v_cmp_lt_u32_e32 vcc, 7, v95
	s_and_b64 exec, vcc, s[20:21]
	s_cbranch_execz .Lp11_m_done
; DI float bflo(unsigned w) { return __uint_as_float(w << 16); }
; DI float bfhi(unsigned w) { return __uint_as_float(w & 0xffff0000u); }
; __global__ void __launch_bounds__(512) fwd_kernel(Params P) {
;     ...
;                     for (int i2 = 1; i2 < w; ++i2) if (t0 - i2 >= 0) { const u32x4 a = *(const u32x4*)(H16 + (size_t)(row0 - i2) * DM + c0); const float r = 1.f / sqrtf(SSQ[3 * (size_t)MT + row0 - i2] * (1.f / DM) + RMS_EPS);
; #pragma unroll
;                         for (int e = 0; e < 4; ++e) { sum[2 * e] += bflo(a[e]) * r; sum[2 * e + 1] += bfhi(a[e]) * r; } }
	v_fmamk_f32 v112, v102, 0x3a800000, v87
	v_mul_f32_e32 v113, 0x4f800000, v112
	v_cmp_gt_f32_e32 vcc, s23, v112
	v_lshlrev_b32_e32 v120, 16, v28
	v_and_b32_e32 v121, 0xffff0000, v28
	v_cndmask_b32_e32 v114, v112, v113, vcc
	v_sqrt_f32_e32 v115, v114
	v_lshlrev_b32_e32 v28, 16, v29
	v_and_b32_e32 v29, 0xffff0000, v29
	v_lshlrev_b32_e32 v112, 16, v30
	v_add_u32_e32 v116, -1, v115
	v_add_u32_e32 v117, 1, v115
	v_fma_f32 v118, -v116, v115, v114
	v_fma_f32 v119, -v117, v115, v114
	v_cmp_ge_f32_e64 s[0:1], 0, v118
	v_and_b32_e32 v113, 0xffff0000, v30
	v_lshlrev_b32_e32 v30, 16, v31
	v_cndmask_b32_e64 v115, v115, v116, s[0:1]
	v_cmp_lt_f32_e64 s[0:1], 0, v119
	v_and_b32_e32 v31, 0xffff0000, v31
	s_nop 0
	v_cndmask_b32_e64 v115, v115, v117, s[0:1]
	v_mul_f32_e32 v116, 0x37800000, v115
	v_cndmask_b32_e32 v115, v115, v116, vcc
	v_cmp_class_f32_e32 vcc, v114, v89
	s_nop 1
	v_cndmask_b32_e32 v114, v115, v114, vcc
	v_div_scale_f32 v115, s[0:1], v114, v114, 1.0
	v_rcp_f32_e32 v116, v115
	v_div_scale_f32 v117, vcc, 1.0, v114, 1.0
	v_fma_f32 v118, -v115, v116, 1.0
	v_fmac_f32_e32 v116, v118, v116
	v_mul_f32_e32 v118, v117, v116
	v_fma_f32 v119, -v115, v118, v117
	v_fmac_f32_e32 v118, v119, v116
	v_fma_f32 v115, -v115, v118, v117
	v_div_fmas_f32 v115, v115, v116, v118
	v_div_fixup_f32 v114, v115, v114, 1.0
	v_pk_fma_f32 v[80:81], v[114:115], v[120:121], v[80:81] op_sel_hi:[0,1,1]
	v_pk_fma_f32 v[78:79], v[114:115], v[28:29], v[78:79] op_sel_hi:[0,1,1]
	v_pk_fma_f32 v[76:77], v[114:115], v[112:113], v[76:77] op_sel_hi:[0,1,1]
	v_pk_fma_f32 v[74:75], v[114:115], v[30:31], v[74:75] op_sel_hi:[0,1,1]
	v_cmp_lt_u32_e32 vcc, 8, v95
	s_and_b64 exec, vcc, s[20:21]
	s_cbranch_execz .Lp11_m_done
	v_fmamk_f32 v112, v103, 0x3a800000, v87
	v_mul_f32_e32 v113, 0x4f800000, v112
	v_cmp_gt_f32_e32 vcc, s23, v112
	v_lshlrev_b32_e32 v120, 16, v32
	v_and_b32_e32 v121, 0xffff0000, v32
	v_cndmask_b32_e32 v114, v112, v113, vcc
	v_sqrt_f32_e32 v115, v114
	v_lshlrev_b32_e32 v32, 16, v33
	v_and_b32_e32 v33, 0xffff0000, v33
	v_lshlrev_b32_e32 v112, 16, v34
	v_add_u32_e32 v116, -1, v115
	v_add_u32_e32 v117, 1, v115
	v_fma_f32 v118, -v116, v115, v114
	v_fma_f32 v119, -v117, v115, v114
	v_cmp_ge_f32_e64 s[0:1], 0, v118
	v_and_b32_e32 v113, 0xffff0000, v34
	v_lshlrev_b32_e32 v34, 16, v35
	v_cndmask_b32_e64 v115, v115, v116, s[0:1]
	v_cmp_lt_f32_e64 s[0:1], 0, v119
	v_and_b32_e32 v35, 0xffff0000, v35
	s_nop 0
	v_cndmask_b32_e64 v115, v115, v117, s[0:1]
	v_mul_f32_e32 v116, 0x37800000, v115
	v_cndmask_b32_e32 v115, v115, v116, vcc
	v_cmp_class_f32_e32 vcc, v114, v89
	s_nop 1
	v_cndmask_b32_e32 v114, v115, v114, vcc
	v_div_scale_f32 v115, s[0:1], v114, v114, 1.0
	v_rcp_f32_e32 v116, v115
	v_div_scale_f32 v117, vcc, 1.0, v114, 1.0
	v_fma_f32 v118, -v115, v116, 1.0
	v_fmac_f32_e32 v116, v118, v116
	v_mul_f32_e32 v118, v117, v116
	v_fma_f32 v119, -v115, v118, v117
	v_fmac_f32_e32 v118, v119, v116
	v_fma_f32 v115, -v115, v118, v117
	v_div_fmas_f32 v115, v115, v116, v118
	v_div_fixup_f32 v114, v115, v114, 1.0
	v_pk_fma_f32 v[80:81], v[114:115], v[120:121], v[80:81] op_sel_hi:[0,1,1]
	v_pk_fma_f32 v[78:79], v[114:115], v[32:33], v[78:79] op_sel_hi:[0,1,1]
	v_pk_fma_f32 v[76:77], v[114:115], v[112:113], v[76:77] op_sel_hi:[0,1,1]
	v_pk_fma_f32 v[74:75], v[114:115], v[34:35], v[74:75] op_sel_hi:[0,1,1]
	v_cmp_lt_u32_e32 vcc, 9, v95
	s_and_b64 exec, vcc, s[20:21]
	s_cbranch_execz .Lp11_m_done
	v_fmamk_f32 v112, v104, 0x3a800000, v87
	v_mul_f32_e32 v113, 0x4f800000, v112
	v_cmp_gt_f32_e32 vcc, s23, v112
	v_lshlrev_b32_e32 v120, 16, v36
	v_and_b32_e32 v121, 0xffff0000, v36
	v_cndmask_b32_e32 v114, v112, v113, vcc
	v_sqrt_f32_e32 v115, v114
	v_lshlrev_b32_e32 v36, 16, v37
	v_and_b32_e32 v37, 0xffff0000, v37
	v_lshlrev_b32_e32 v112, 16, v38
	v_add_u32_e32 v116, -1, v115
	v_add_u32_e32 v117, 1, v115
	v_fma_f32 v118, -v116, v115, v114
	v_fma_f32 v119, -v117, v115, v114
	v_cmp_ge_f32_e64 s[0:1], 0, v118
	v_and_b32_e32 v113, 0xffff0000, v38
	v_lshlrev_b32_e32 v38, 16, v39
	v_cndmask_b32_e64 v115, v115, v116, s[0:1]
	v_cmp_lt_f32_e64 s[0:1], 0, v119
	v_and_b32_e32 v39, 0xffff0000, v39
	s_nop 0
	v_cndmask_b32_e64 v115, v115, v117, s[0:1]
	v_mul_f32_e32 v116, 0x37800000, v115
	v_cndmask_b32_e32 v115, v115, v116, vcc
	v_cmp_class_f32_e32 vcc, v114, v89
	s_nop 1
	v_cndmask_b32_e32 v114, v115, v114, vcc
	v_div_scale_f32 v115, s[0:1], v114, v114, 1.0
	v_rcp_f32_e32 v116, v115
	v_div_scale_f32 v117, vcc, 1.0, v114, 1.0
	v_fma_f32 v118, -v115, v116, 1.0
	v_fmac_f32_e32 v116, v118, v116
	v_mul_f32_e32 v118, v117, v116
	v_fma_f32 v119, -v115, v118, v117
	v_fmac_f32_e32 v118, v119, v116
	v_fma_f32 v115, -v115, v118, v117
	v_div_fmas_f32 v115, v115, v116, v118
	v_div_fixup_f32 v114, v115, v114, 1.0
	v_pk_fma_f32 v[80:81], v[114:115], v[120:121], v[80:81] op_sel_hi:[0,1,1]
	v_pk_fma_f32 v[78:79], v[114:115], v[36:37], v[78:79] op_sel_hi:[0,1,1]
	v_pk_fma_f32 v[76:77], v[114:115], v[112:113], v[76:77] op_sel_hi:[0,1,1]
	v_pk_fma_f32 v[74:75], v[114:115], v[38:39], v[74:75] op_sel_hi:[0,1,1]
	v_cmp_lt_u32_e32 vcc, 10, v95
	s_and_b64 exec, vcc, s[20:21]
	s_cbranch_execz .Lp11_m_done
; DI float bflo(unsigned w) { return __uint_as_float(w << 16); }
; DI float bfhi(unsigned w) { return __uint_as_float(w & 0xffff0000u); }
; __global__ void __launch_bounds__(512) fwd_kernel(Params P) {
;     ...
;                     for (int i2 = 1; i2 < w; ++i2) if (t0 - i2 >= 0) { const u32x4 a = *(const u32x4*)(H16 + (size_t)(row0 - i2) * DM + c0); const float r = 1.f / sqrtf(SSQ[3 * (size_t)MT + row0 - i2] * (1.f / DM) + RMS_EPS);
; #pragma unroll
;                         for (int e = 0; e < 4; ++e) { sum[2 * e] += bflo(a[e]) * r; sum[2 * e + 1] += bfhi(a[e]) * r; } }
	v_fmamk_f32 v112, v105, 0x3a800000, v87
	v_mul_f32_e32 v113, 0x4f800000, v112
	v_cmp_gt_f32_e32 vcc, s23, v112
	v_lshlrev_b32_e32 v120, 16, v40
	v_and_b32_e32 v121, 0xffff0000, v40
	v_cndmask_b32_e32 v114, v112, v113, vcc
	v_sqrt_f32_e32 v115, v114
	v_lshlrev_b32_e32 v40, 16, v41
	v_and_b32_e32 v41, 0xffff0000, v41
	v_lshlrev_b32_e32 v112, 16, v42
	v_add_u32_e32 v116, -1, v115
	v_add_u32_e32 v117, 1, v115
	v_fma_f32 v118, -v116, v115, v114
	v_fma_f32 v119, -v117, v115, v114
	v_cmp_ge_f32_e64 s[0:1], 0, v118
	v_and_b32_e32 v113, 0xffff0000, v42
	v_lshlrev_b32_e32 v42, 16, v43
	v_cndmask_b32_e64 v115, v115, v116, s[0:1]
	v_cmp_lt_f32_e64 s[0:1], 0, v119
	v_and_b32_e32 v43, 0xffff0000, v43
	s_nop 0
	v_cndmask_b32_e64 v115, v115, v117, s[0:1]
	v_mul_f32_e32 v116, 0x37800000, v115
	v_cndmask_b32_e32 v115, v115, v116, vcc
	v_cmp_class_f32_e32 vcc, v114, v89
	s_nop 1
	v_cndmask_b32_e32 v114, v115, v114, vcc
	v_div_scale_f32 v115, s[0:1], v114, v114, 1.0
	v_rcp_f32_e32 v116, v115
	v_div_scale_f32 v117, vcc, 1.0, v114, 1.0
	v_fma_f32 v118, -v115, v116, 1.0
	v_fmac_f32_e32 v116, v118, v116
	v_mul_f32_e32 v118, v117, v116
	v_fma_f32 v119, -v115, v118, v117
	v_fmac_f32_e32 v118, v119, v116
	v_fma_f32 v115, -v115, v118, v117
	v_div_fmas_f32 v115, v115, v116, v118
	v_div_fixup_f32 v114, v115, v114, 1.0
	v_pk_fma_f32 v[80:81], v[114:115], v[120:121], v[80:81] op_sel_hi:[0,1,1]
	v_pk_fma_f32 v[78:79], v[114:115], v[40:41], v[78:79] op_sel_hi:[0,1,1]
	v_pk_fma_f32 v[76:77], v[114:115], v[112:113], v[76:77] op_sel_hi:[0,1,1]
	v_pk_fma_f32 v[74:75], v[114:115], v[42:43], v[74:75] op_sel_hi:[0,1,1]
	v_cmp_lt_u32_e32 vcc, 11, v95
	s_and_b64 exec, vcc, s[20:21]
	s_cbranch_execz .Lp11_m_done
	v_fmamk_f32 v112, v106, 0x3a800000, v87
	v_mul_f32_e32 v113, 0x4f800000, v112
	v_cmp_gt_f32_e32 vcc, s23, v112
	v_lshlrev_b32_e32 v120, 16, v44
	v_and_b32_e32 v121, 0xffff0000, v44
	v_cndmask_b32_e32 v114, v112, v113, vcc
	v_sqrt_f32_e32 v115, v114
	v_lshlrev_b32_e32 v44, 16, v45
	v_and_b32_e32 v45, 0xffff0000, v45
	v_lshlrev_b32_e32 v112, 16, v46
	v_add_u32_e32 v116, -1, v115
	v_add_u32_e32 v117, 1, v115
	v_fma_f32 v118, -v116, v115, v114
	v_fma_f32 v119, -v117, v115, v114
	v_cmp_ge_f32_e64 s[0:1], 0, v118
	v_and_b32_e32 v113, 0xffff0000, v46
	v_lshlrev_b32_e32 v46, 16, v47
	v_cndmask_b32_e64 v115, v115, v116, s[0:1]
	v_cmp_lt_f32_e64 s[0:1], 0, v119
	v_and_b32_e32 v47, 0xffff0000, v47
	s_nop 0
	v_cndmask_b32_e64 v115, v115, v117, s[0:1]
	v_mul_f32_e32 v116, 0x37800000, v115
	v_cndmask_b32_e32 v115, v115, v116, vcc
	v_cmp_class_f32_e32 vcc, v114, v89
	s_nop 1
	v_cndmask_b32_e32 v114, v115, v114, vcc
	v_div_scale_f32 v115, s[0:1], v114, v114, 1.0
	v_rcp_f32_e32 v116, v115
	v_div_scale_f32 v117, vcc, 1.0, v114, 1.0
	v_fma_f32 v118, -v115, v116, 1.0
	v_fmac_f32_e32 v116, v118, v116
	v_mul_f32_e32 v118, v117, v116
	v_fma_f32 v119, -v115, v118, v117
	v_fmac_f32_e32 v118, v119, v116
	v_fma_f32 v115, -v115, v118, v117
	v_div_fmas_f32 v115, v115, v116, v118
	v_div_fixup_f32 v114, v115, v114, 1.0
	v_pk_fma_f32 v[80:81], v[114:115], v[120:121], v[80:81] op_sel_hi:[0,1,1]
	v_pk_fma_f32 v[78:79], v[114:115], v[44:45], v[78:79] op_sel_hi:[0,1,1]
	v_pk_fma_f32 v[76:77], v[114:115], v[112:113], v[76:77] op_sel_hi:[0,1,1]
	v_pk_fma_f32 v[74:75], v[114:115], v[46:47], v[74:75] op_sel_hi:[0,1,1]
	v_cmp_lt_u32_e32 vcc, 12, v95
	s_and_b64 exec, vcc, s[20:21]
	s_cbranch_execz .Lp11_m_done
	v_fmamk_f32 v112, v107, 0x3a800000, v87
	v_mul_f32_e32 v113, 0x4f800000, v112
	v_cmp_gt_f32_e32 vcc, s23, v112
	v_lshlrev_b32_e32 v120, 16, v48
	v_and_b32_e32 v121, 0xffff0000, v48
	v_cndmask_b32_e32 v114, v112, v113, vcc
	v_sqrt_f32_e32 v115, v114
	v_lshlrev_b32_e32 v48, 16, v49
	v_and_b32_e32 v49, 0xffff0000, v49
	v_lshlrev_b32_e32 v112, 16, v50
	v_add_u32_e32 v116, -1, v115
	v_add_u32_e32 v117, 1, v115
	v_fma_f32 v118, -v116, v115, v114
	v_fma_f32 v119, -v117, v115, v114
	v_cmp_ge_f32_e64 s[0:1], 0, v118
	v_and_b32_e32 v113, 0xffff0000, v50
	v_lshlrev_b32_e32 v50, 16, v51
	v_cndmask_b32_e64 v115, v115, v116, s[0:1]
	v_cmp_lt_f32_e64 s[0:1], 0, v119
	v_and_b32_e32 v51, 0xffff0000, v51
	s_nop 0
	v_cndmask_b32_e64 v115, v115, v117, s[0:1]
	v_mul_f32_e32 v116, 0x37800000, v115
	v_cndmask_b32_e32 v115, v115, v116, vcc
	v_cmp_class_f32_e32 vcc, v114, v89
	s_nop 1
	v_cndmask_b32_e32 v114, v115, v114, vcc
	v_div_scale_f32 v115, s[0:1], v114, v114, 1.0
	v_rcp_f32_e32 v116, v115
	v_div_scale_f32 v117, vcc, 1.0, v114, 1.0
	v_fma_f32 v118, -v115, v116, 1.0
	v_fmac_f32_e32 v116, v118, v116
	v_mul_f32_e32 v118, v117, v116
	v_fma_f32 v119, -v115, v118, v117
	v_fmac_f32_e32 v118, v119, v116
	v_fma_f32 v115, -v115, v118, v117
	v_div_fmas_f32 v115, v115, v116, v118
	v_div_fixup_f32 v114, v115, v114, 1.0
	v_pk_fma_f32 v[80:81], v[114:115], v[120:121], v[80:81] op_sel_hi:[0,1,1]
	v_pk_fma_f32 v[78:79], v[114:115], v[48:49], v[78:79] op_sel_hi:[0,1,1]
	v_pk_fma_f32 v[76:77], v[114:115], v[112:113], v[76:77] op_sel_hi:[0,1,1]
	v_pk_fma_f32 v[74:75], v[114:115], v[50:51], v[74:75] op_sel_hi:[0,1,1]
	v_cmp_lt_u32_e32 vcc, 13, v95
	s_and_b64 exec, vcc, s[20:21]
	s_cbranch_execz .Lp11_m_done
; DI float bflo(unsigned w) { return __uint_as_float(w << 16); }
; DI float bfhi(unsigned w) { return __uint_as_float(w & 0xffff0000u); }
; __global__ void __launch_bounds__(512) fwd_kernel(Params P) {
;     ...
;                     for (int i2 = 1; i2 < w; ++i2) if (t0 - i2 >= 0) { const u32x4 a = *(const u32x4*)(H16 + (size_t)(row0 - i2) * DM + c0); const float r = 1.f / sqrtf(SSQ[3 * (size_t)MT + row0 - i2] * (1.f / DM) + RMS_EPS);
; #pragma unroll
;                         for (int e = 0; e < 4; ++e) { sum[2 * e] += bflo(a[e]) * r; sum[2 * e + 1] += bfhi(a[e]) * r; } }
;                     for (int tb = 0; tb < 32; tb += 8) {
;                         u32x4 cn[8], co[8]; float rn[8], ro[8];
; #pragma unroll
;                         for (int k = 0; k < 8; ++k) { const int tt = tb + k, t = t0 + tt; const bool old = (tt > 0 && t - w >= 0);
;                             cn[k] = *(const u32x4*)(H16 + (size_t)(row0 + tt) * DM + c0); rn[k] = 1.f / sqrtf(SSQ[3 * (size_t)MT + row0 + tt] * (1.f / DM) + RMS_EPS);
;                             co[k] = old ? *(const u32x4*)(H16 + (size_t)(row0 + tt - w) * DM + c0) : (u32x4){0u, 0u, 0u, 0u}; ro[k] = old ? 1.f / sqrtf(SSQ[3 * (size_t)MT + row0 + tt - w] * (1.f / DM) + RMS_EPS) : 0.f; }
	v_fmamk_f32 v112, v108, 0x3a800000, v87
	v_mul_f32_e32 v113, 0x4f800000, v112
	v_cmp_gt_f32_e32 vcc, s23, v112
	v_lshlrev_b32_e32 v120, 16, v52
	v_and_b32_e32 v121, 0xffff0000, v52
	v_cndmask_b32_e32 v114, v112, v113, vcc
	v_sqrt_f32_e32 v115, v114
	v_lshlrev_b32_e32 v52, 16, v53
	v_and_b32_e32 v53, 0xffff0000, v53
	v_lshlrev_b32_e32 v112, 16, v54
	v_add_u32_e32 v116, -1, v115
	v_add_u32_e32 v117, 1, v115
	v_fma_f32 v118, -v116, v115, v114
	v_fma_f32 v119, -v117, v115, v114
	v_cmp_ge_f32_e64 s[0:1], 0, v118
	v_and_b32_e32 v113, 0xffff0000, v54
	v_lshlrev_b32_e32 v54, 16, v55
	v_cndmask_b32_e64 v115, v115, v116, s[0:1]
	v_cmp_lt_f32_e64 s[0:1], 0, v119
	v_and_b32_e32 v55, 0xffff0000, v55
	s_nop 0
	v_cndmask_b32_e64 v115, v115, v117, s[0:1]
	v_mul_f32_e32 v116, 0x37800000, v115
	v_cndmask_b32_e32 v115, v115, v116, vcc
	v_cmp_class_f32_e32 vcc, v114, v89
	s_nop 1
	v_cndmask_b32_e32 v114, v115, v114, vcc
	v_div_scale_f32 v115, s[0:1], v114, v114, 1.0
	v_rcp_f32_e32 v116, v115
	v_div_scale_f32 v117, vcc, 1.0, v114, 1.0
	v_fma_f32 v118, -v115, v116, 1.0
	v_fmac_f32_e32 v116, v118, v116
	v_mul_f32_e32 v118, v117, v116
	v_fma_f32 v119, -v115, v118, v117
	v_fmac_f32_e32 v118, v119, v116
	v_fma_f32 v115, -v115, v118, v117
	v_div_fmas_f32 v115, v115, v116, v118
	v_div_fixup_f32 v114, v115, v114, 1.0
	v_pk_fma_f32 v[80:81], v[114:115], v[120:121], v[80:81] op_sel_hi:[0,1,1]
	v_pk_fma_f32 v[78:79], v[114:115], v[52:53], v[78:79] op_sel_hi:[0,1,1]
	v_pk_fma_f32 v[76:77], v[114:115], v[112:113], v[76:77] op_sel_hi:[0,1,1]
	v_pk_fma_f32 v[74:75], v[114:115], v[54:55], v[74:75] op_sel_hi:[0,1,1]
	v_cmp_lt_u32_e32 vcc, 14, v95
	s_and_b64 exec, vcc, s[20:21]
	s_cbranch_execz .Lp11_m_done
	v_fmamk_f32 v112, v109, 0x3a800000, v87
	v_mul_f32_e32 v113, 0x4f800000, v112
	v_cmp_gt_f32_e32 vcc, s23, v112
	v_lshlrev_b32_e32 v120, 16, v56
	v_and_b32_e32 v121, 0xffff0000, v56
	v_cndmask_b32_e32 v114, v112, v113, vcc
	v_sqrt_f32_e32 v115, v114
	v_lshlrev_b32_e32 v56, 16, v57
	v_and_b32_e32 v57, 0xffff0000, v57
	v_lshlrev_b32_e32 v112, 16, v58
	v_add_u32_e32 v116, -1, v115
	v_add_u32_e32 v117, 1, v115
	v_fma_f32 v118, -v116, v115, v114
	v_fma_f32 v119, -v117, v115, v114
	v_cmp_ge_f32_e64 s[0:1], 0, v118
	v_and_b32_e32 v113, 0xffff0000, v58
	v_lshlrev_b32_e32 v58, 16, v59
	v_cndmask_b32_e64 v115, v115, v116, s[0:1]
	v_cmp_lt_f32_e64 s[0:1], 0, v119
	v_and_b32_e32 v59, 0xffff0000, v59
	s_nop 0
	v_cndmask_b32_e64 v115, v115, v117, s[0:1]
	v_mul_f32_e32 v116, 0x37800000, v115
	v_cndmask_b32_e32 v115, v115, v116, vcc
	v_cmp_class_f32_e32 vcc, v114, v89
	s_nop 1
	v_cndmask_b32_e32 v114, v115, v114, vcc
	v_div_scale_f32 v115, s[0:1], v114, v114, 1.0
	v_rcp_f32_e32 v116, v115
	v_div_scale_f32 v117, vcc, 1.0, v114, 1.0
	v_fma_f32 v118, -v115, v116, 1.0
	v_fmac_f32_e32 v116, v118, v116
	v_mul_f32_e32 v118, v117, v116
	v_fma_f32 v119, -v115, v118, v117
	v_fmac_f32_e32 v118, v119, v116
	v_fma_f32 v115, -v115, v118, v117
	v_div_fmas_f32 v115, v115, v116, v118
	v_div_fixup_f32 v114, v115, v114, 1.0
	v_pk_fma_f32 v[80:81], v[114:115], v[120:121], v[80:81] op_sel_hi:[0,1,1]
	v_pk_fma_f32 v[78:79], v[114:115], v[56:57], v[78:79] op_sel_hi:[0,1,1]
	v_pk_fma_f32 v[76:77], v[114:115], v[112:113], v[76:77] op_sel_hi:[0,1,1]
	v_pk_fma_f32 v[74:75], v[114:115], v[58:59], v[74:75] op_sel_hi:[0,1,1]
	v_cmp_lt_u32_e32 vcc, 15, v95
	s_and_b64 exec, vcc, s[20:21]
	s_cbranch_execz .Lp11_m_done
	v_fmamk_f32 v112, v110, 0x3a800000, v87
	v_mul_f32_e32 v113, 0x4f800000, v112
	v_cmp_gt_f32_e32 vcc, s23, v112
	v_lshlrev_b32_e32 v120, 16, v60
	v_and_b32_e32 v121, 0xffff0000, v60
	v_cndmask_b32_e32 v114, v112, v113, vcc
	v_sqrt_f32_e32 v115, v114
	v_lshlrev_b32_e32 v60, 16, v61
	v_and_b32_e32 v61, 0xffff0000, v61
	v_lshlrev_b32_e32 v112, 16, v62
	v_add_u32_e32 v116, -1, v115
	v_add_u32_e32 v117, 1, v115
	v_fma_f32 v118, -v116, v115, v114
	v_fma_f32 v119, -v117, v115, v114
	v_cmp_ge_f32_e64 s[0:1], 0, v118
	v_and_b32_e32 v113, 0xffff0000, v62
	v_lshlrev_b32_e32 v62, 16, v63
	v_cndmask_b32_e64 v115, v115, v116, s[0:1]
	v_cmp_lt_f32_e64 s[0:1], 0, v119
	v_and_b32_e32 v63, 0xffff0000, v63
	s_nop 0
	v_cndmask_b32_e64 v115, v115, v117, s[0:1]
	v_mul_f32_e32 v116, 0x37800000, v115
	v_cndmask_b32_e32 v115, v115, v116, vcc
	v_cmp_class_f32_e32 vcc, v114, v89
	s_nop 1
	v_cndmask_b32_e32 v114, v115, v114, vcc
	v_div_scale_f32 v115, s[0:1], v114, v114, 1.0
	v_rcp_f32_e32 v116, v115
	v_div_scale_f32 v117, vcc, 1.0, v114, 1.0
	v_fma_f32 v118, -v115, v116, 1.0
	v_fmac_f32_e32 v116, v118, v116
	v_mul_f32_e32 v118, v117, v116
	v_fma_f32 v119, -v115, v118, v117
	v_fmac_f32_e32 v118, v119, v116
	v_fma_f32 v115, -v115, v118, v117
	v_div_fmas_f32 v115, v115, v116, v118
	v_div_fixup_f32 v114, v115, v114, 1.0
	v_pk_fma_f32 v[80:81], v[114:115], v[120:121], v[80:81] op_sel_hi:[0,1,1]
	v_pk_fma_f32 v[78:79], v[114:115], v[60:61], v[78:79] op_sel_hi:[0,1,1]
	v_pk_fma_f32 v[76:77], v[114:115], v[112:113], v[76:77] op_sel_hi:[0,1,1]
	v_pk_fma_f32 v[74:75], v[114:115], v[62:63], v[74:75] op_sel_hi:[0,1,1]
.Lp11_m_done:
	s_mov_b64 exec, s[4:5]
	v_lshlrev_b32_e32 v0, 11, v95
	v_sub_co_u32_e32 v68, vcc, v64, v0
	v_lshlrev_b32_e32 v0, 2, v95
	s_nop 0
	v_subbrev_co_u32_e32 v69, vcc, 0, v65, vcc
	v_sub_co_u32_e32 v70, vcc, v66, v0
	s_mov_b32 s20, -8
	s_nop 0
	v_subbrev_co_u32_e32 v71, vcc, 0, v67, vcc
	s_branch .LBB0_1285

; __global__ void __launch_bounds__(512) fwd_kernel(Params P) {
;     ...
;                     for (int tb = 0; tb < 32; tb += 8) {
;                         u32x4 cn[8], co[8]; float rn[8], ro[8];
; #pragma unroll
;                         for (int k = 0; k < 8; ++k) { const int tt = tb + k, t = t0 + tt; const bool old = (tt > 0 && t - w >= 0);
;                             cn[k] = *(const u32x4*)(H16 + (size_t)(row0 + tt) * DM + c0); rn[k] = 1.f / sqrtf(SSQ[3 * (size_t)MT + row0 + tt] * (1.f / DM) + RMS_EPS);
;                             co[k] = old ? *(const u32x4*)(H16 + (size_t)(row0 + tt - w) * DM + c0) : (u32x4){0u, 0u, 0u, 0u}; ro[k] = old ? 1.f / sqrtf(SSQ[3 * (size_t)MT + row0 + tt - w] * (1.f / DM) + RMS_EPS) : 0.f; }
.LBB0_1285:
	v_lshl_add_u64 v[72:73], s[34:35], 0, v[64:65]
	v_lshl_add_u64 v[114:115], s[34:35], 0, v[66:67]
	v_lshl_add_u64 v[118:119], s[34:35], 0, v[68:69]
	v_lshl_add_u64 v[120:121], s[34:35], 0, v[70:71]
	s_mov_b32 s0, 0x3400000
	s_mov_b32 s1, 0
	s_mov_b32 s100, 0x1000
	s_mov_b32 s101, 0
	v_add_u32_e32 v97, s20, v93
	v_lshl_add_u64 v[114:115], v[114:115], 0, s[0:1]
	v_lshl_add_u64 v[120:121], v[120:121], 0, s[0:1]
	s_mov_b32 s0, s24
	v_lshl_add_u64 v[116:117], v[72:73], 0, s[0:1]
	v_lshl_add_u64 v[118:119], v[118:119], 0, s[0:1]
	global_load_dwordx4 v[0:3], v[116:117], off
	global_load_dword v99, v[114:115], off
	global_load_dwordx4 v[4:7], v[116:117], off offset:2048
	global_load_dword v108, v[114:115], off offset:4
	v_lshl_add_u64 v[116:117], v[116:117], 0, s[100:101]
	global_load_dwordx4 v[12:15], v[116:117], off
	global_load_dword v106, v[114:115], off offset:8
	global_load_dwordx4 v[24:27], v[116:117], off offset:2048
	global_load_dword v104, v[114:115], off offset:12
	v_lshl_add_u64 v[116:117], v[116:117], 0, s[100:101]
	global_load_dwordx4 v[28:31], v[116:117], off
	global_load_dword v102, v[114:115], off offset:16
	global_load_dwordx4 v[36:39], v[116:117], off offset:2048
	global_load_dword v100, v[114:115], off offset:20
	v_lshl_add_u64 v[116:117], v[116:117], 0, s[100:101]
	global_load_dwordx4 v[44:47], v[116:117], off
	global_load_dword v98, v[114:115], off offset:24
	global_load_dwordx4 v[56:59], v[116:117], off offset:2048
	global_load_dword v112, v[114:115], off offset:28
	v_add_u32_e32 v113, 8, v97
	v_add_u32_e32 v101, 9, v97
	v_add_u32_e32 v103, 10, v97
	v_add_u32_e32 v105, 11, v97
	v_add_u32_e32 v107, 12, v97
	v_add_u32_e32 v109, 13, v97
	v_add_u32_e32 v110, 14, v97
	v_add_u32_e32 v111, 15, v97
	v_mov_b32_e32 v8, 0
	v_mov_b32_e32 v9, 0
	v_mov_b32_e32 v10, 0
	v_mov_b32_e32 v11, 0
	v_mov_b32_e32 v88, 0
	v_mov_b32_e32 v16, 0
	v_mov_b32_e32 v17, 0
	v_mov_b32_e32 v18, 0
	v_mov_b32_e32 v19, 0
	v_mov_b32_e32 v82, 0
	v_mov_b32_e32 v20, 0
	v_mov_b32_e32 v21, 0
	v_mov_b32_e32 v22, 0
	v_mov_b32_e32 v23, 0
	v_mov_b32_e32 v90, 0
	v_mov_b32_e32 v32, 0
	v_mov_b32_e32 v33, 0
	v_mov_b32_e32 v34, 0
	v_mov_b32_e32 v35, 0
	v_mov_b32_e32 v84, 0
	v_mov_b32_e32 v40, 0
	v_mov_b32_e32 v41, 0
	v_mov_b32_e32 v42, 0
	v_mov_b32_e32 v43, 0
	v_mov_b32_e32 v94, 0
	v_mov_b32_e32 v48, 0
	v_mov_b32_e32 v49, 0
	v_mov_b32_e32 v50, 0
	v_mov_b32_e32 v51, 0
	v_mov_b32_e32 v86, 0
	v_mov_b32_e32 v52, 0
	v_mov_b32_e32 v53, 0
	v_mov_b32_e32 v54, 0
	v_mov_b32_e32 v55, 0
	v_mov_b32_e32 v96, 0
	v_mov_b32_e32 v60, 0
	v_mov_b32_e32 v61, 0
	v_mov_b32_e32 v62, 0
	v_mov_b32_e32 v63, 0
	v_mov_b32_e32 v92, 0
	s_cmp_lg_u32 s20, -8
	s_cselect_b64 s[0:1], -1, 0
	v_cmp_ge_u32_e32 vcc, v113, v95
	s_and_b64 vcc, s[0:1], vcc
	s_and_saveexec_b64 s[4:5], vcc
	global_load_dword v88, v[120:121], off
	global_load_dwordx4 v[8:11], v[118:119], off
	s_or_b64 exec, exec, s[4:5]
	v_cmp_ge_u32_e32 vcc, v101, v95
	s_and_saveexec_b64 s[4:5], vcc
	global_load_dword v82, v[120:121], off offset:4
	global_load_dwordx4 v[16:19], v[118:119], off offset:2048
	s_or_b64 exec, exec, s[4:5]
	v_lshl_add_u64 v[118:119], v[118:119], 0, s[100:101]
	v_cmp_ge_u32_e32 vcc, v103, v95
	s_and_saveexec_b64 s[4:5], vcc
	global_load_dword v90, v[120:121], off offset:8
	global_load_dwordx4 v[20:23], v[118:119], off
	s_or_b64 exec, exec, s[4:5]
	v_cmp_ge_u32_e32 vcc, v105, v95
	s_and_saveexec_b64 s[4:5], vcc
	global_load_dword v84, v[120:121], off offset:12
	global_load_dwordx4 v[32:35], v[118:119], off offset:2048
	s_or_b64 exec, exec, s[4:5]
	v_lshl_add_u64 v[118:119], v[118:119], 0, s[100:101]
	v_cmp_ge_u32_e32 vcc, v107, v95
	s_and_saveexec_b64 s[4:5], vcc
	global_load_dword v94, v[120:121], off offset:16
	global_load_dwordx4 v[40:43], v[118:119], off
	s_or_b64 exec, exec, s[4:5]
	v_cmp_ge_u32_e32 vcc, v109, v95
	s_and_saveexec_b64 s[4:5], vcc
	global_load_dword v86, v[120:121], off offset:20
	global_load_dwordx4 v[48:51], v[118:119], off offset:2048
	s_or_b64 exec, exec, s[4:5]
	v_lshl_add_u64 v[118:119], v[118:119], 0, s[100:101]
	v_cmp_ge_u32_e32 vcc, v110, v95
	s_and_saveexec_b64 s[4:5], vcc
	global_load_dword v96, v[120:121], off offset:24
	global_load_dwordx4 v[52:55], v[118:119], off
	s_or_b64 exec, exec, s[4:5]
	v_cmp_ge_u32_e32 vcc, v111, v95
	s_and_saveexec_b64 s[4:5], vcc
	global_load_dword v92, v[120:121], off offset:28
	global_load_dwordx4 v[60:63], v[118:119], off offset:2048
	s_or_b64 exec, exec, s[4:5]
	s_waitcnt vmcnt(0)
	s_cmp_lg_u32 s20, -8
	s_cselect_b64 s[100:101], -1, 0
	v_cmp_ge_u32_e32 vcc, v113, v95
	s_and_b64 vcc, s[100:101], vcc
	s_and_saveexec_b64 s[4:5], vcc
	s_cbranch_execz .Lp11_ro0
	v_fmamk_f32 v88, v88, 0x3a800000, v87
	v_mul_f32_e32 v113, 0x4f800000, v88
	v_cmp_gt_f32_e32 vcc, s23, v88
	s_nop 1
	v_cndmask_b32_e32 v88, v88, v113, vcc
	v_sqrt_f32_e32 v113, v88
	s_nop 0
	v_add_u32_e32 v114, -1, v113
	v_add_u32_e32 v115, 1, v113
	v_fma_f32 v116, -v114, v113, v88
	v_fma_f32 v117, -v115, v113, v88
	v_cmp_ge_f32_e64 s[0:1], 0, v116
	s_nop 1
	v_cndmask_b32_e64 v113, v113, v114, s[0:1]
	v_cmp_lt_f32_e64 s[0:1], 0, v117
	s_nop 1
	v_cndmask_b32_e64 v113, v113, v115, s[0:1]
	v_mul_f32_e32 v114, 0x37800000, v113
	v_cndmask_b32_e32 v113, v113, v114, vcc
	v_cmp_class_f32_e32 vcc, v88, v89
	s_nop 1
	v_cndmask_b32_e32 v88, v113, v88, vcc
	v_div_scale_f32 v113, s[0:1], v88, v88, 1.0
	v_rcp_f32_e32 v114, v113
	v_div_scale_f32 v115, vcc, 1.0, v88, 1.0
	v_fma_f32 v116, -v113, v114, 1.0
	v_fmac_f32_e32 v114, v116, v114
	v_mul_f32_e32 v116, v115, v114
	v_fma_f32 v117, -v113, v116, v115
	v_fmac_f32_e32 v116, v117, v114
	v_fma_f32 v113, -v113, v116, v115
	v_div_fmas_f32 v113, v113, v114, v116
	v_div_fixup_f32 v88, v113, v88, 1.0
; __global__ void __launch_bounds__(512) fwd_kernel(Params P) {
;     ...
;                             co[k] = old ? *(const u32x4*)(H16 + (size_t)(row0 + tt - w) * DM + c0) : (u32x4){0u, 0u, 0u, 0u}; ro[k] = old ? 1.f / sqrtf(SSQ[3 * (size_t)MT + row0 + tt - w] * (1.f / DM) + RMS_EPS) : 0.f; }
.Lp11_ro0:
	s_or_b64 exec, exec, s[4:5]
	v_cmp_ge_u32_e32 vcc, v101, v95
	s_and_saveexec_b64 s[4:5], vcc
	s_cbranch_execz .Lp11_ro1
	v_fmamk_f32 v82, v82, 0x3a800000, v87
	v_mul_f32_e32 v113, 0x4f800000, v82
	v_cmp_gt_f32_e32 vcc, s23, v82
	s_nop 1
	v_cndmask_b32_e32 v82, v82, v113, vcc
	v_sqrt_f32_e32 v113, v82
	s_nop 0
	v_add_u32_e32 v114, -1, v113
	v_add_u32_e32 v115, 1, v113
	v_fma_f32 v116, -v114, v113, v82
	v_fma_f32 v117, -v115, v113, v82
	v_cmp_ge_f32_e64 s[0:1], 0, v116
	s_nop 1
	v_cndmask_b32_e64 v113, v113, v114, s[0:1]
	v_cmp_lt_f32_e64 s[0:1], 0, v117
	s_nop 1
	v_cndmask_b32_e64 v113, v113, v115, s[0:1]
	v_mul_f32_e32 v114, 0x37800000, v113
	v_cndmask_b32_e32 v113, v113, v114, vcc
	v_cmp_class_f32_e32 vcc, v82, v89
	s_nop 1
	v_cndmask_b32_e32 v82, v113, v82, vcc
	v_div_scale_f32 v113, s[0:1], v82, v82, 1.0
	v_rcp_f32_e32 v114, v113
	v_div_scale_f32 v115, vcc, 1.0, v82, 1.0
	v_fma_f32 v116, -v113, v114, 1.0
	v_fmac_f32_e32 v114, v116, v114
	v_mul_f32_e32 v116, v115, v114
	v_fma_f32 v117, -v113, v116, v115
	v_fmac_f32_e32 v116, v117, v114
	v_fma_f32 v113, -v113, v116, v115
	v_div_fmas_f32 v113, v113, v114, v116
	v_div_fixup_f32 v82, v113, v82, 1.0
.Lp11_ro1:
	s_or_b64 exec, exec, s[4:5]
	v_cmp_ge_u32_e32 vcc, v103, v95
	s_and_saveexec_b64 s[4:5], vcc
	s_cbranch_execz .Lp11_ro2
	v_fmamk_f32 v90, v90, 0x3a800000, v87
	v_mul_f32_e32 v113, 0x4f800000, v90
	v_cmp_gt_f32_e32 vcc, s23, v90
	s_nop 1
	v_cndmask_b32_e32 v90, v90, v113, vcc
	v_sqrt_f32_e32 v113, v90
	s_nop 0
	v_add_u32_e32 v114, -1, v113
	v_add_u32_e32 v115, 1, v113
	v_fma_f32 v116, -v114, v113, v90
	v_fma_f32 v117, -v115, v113, v90
	v_cmp_ge_f32_e64 s[0:1], 0, v116
	s_nop 1
	v_cndmask_b32_e64 v113, v113, v114, s[0:1]
	v_cmp_lt_f32_e64 s[0:1], 0, v117
	s_nop 1
	v_cndmask_b32_e64 v113, v113, v115, s[0:1]
	v_mul_f32_e32 v114, 0x37800000, v113
	v_cndmask_b32_e32 v113, v113, v114, vcc
	v_cmp_class_f32_e32 vcc, v90, v89
	s_nop 1
	v_cndmask_b32_e32 v90, v113, v90, vcc
	v_div_scale_f32 v113, s[0:1], v90, v90, 1.0
	v_rcp_f32_e32 v114, v113
	v_div_scale_f32 v115, vcc, 1.0, v90, 1.0
	v_fma_f32 v116, -v113, v114, 1.0
	v_fmac_f32_e32 v114, v116, v114
	v_mul_f32_e32 v116, v115, v114
	v_fma_f32 v117, -v113, v116, v115
	v_fmac_f32_e32 v116, v117, v114
	v_fma_f32 v113, -v113, v116, v115
	v_div_fmas_f32 v113, v113, v114, v116
	v_div_fixup_f32 v90, v113, v90, 1.0
.Lp11_ro2:
	s_or_b64 exec, exec, s[4:5]
	v_cmp_ge_u32_e32 vcc, v105, v95
	s_and_saveexec_b64 s[4:5], vcc
	s_cbranch_execz .Lp11_ro3
	v_fmamk_f32 v84, v84, 0x3a800000, v87
	v_mul_f32_e32 v113, 0x4f800000, v84
	v_cmp_gt_f32_e32 vcc, s23, v84
	s_nop 1
	v_cndmask_b32_e32 v84, v84, v113, vcc
	v_sqrt_f32_e32 v113, v84
	s_nop 0
	v_add_u32_e32 v114, -1, v113
	v_add_u32_e32 v115, 1, v113
	v_fma_f32 v116, -v114, v113, v84
	v_fma_f32 v117, -v115, v113, v84
	v_cmp_ge_f32_e64 s[0:1], 0, v116
	s_nop 1
	v_cndmask_b32_e64 v113, v113, v114, s[0:1]
	v_cmp_lt_f32_e64 s[0:1], 0, v117
	s_nop 1
	v_cndmask_b32_e64 v113, v113, v115, s[0:1]
	v_mul_f32_e32 v114, 0x37800000, v113
	v_cndmask_b32_e32 v113, v113, v114, vcc
	v_cmp_class_f32_e32 vcc, v84, v89
	s_nop 1
	v_cndmask_b32_e32 v84, v113, v84, vcc
	v_div_scale_f32 v113, s[0:1], v84, v84, 1.0
	v_rcp_f32_e32 v114, v113
	v_div_scale_f32 v115, vcc, 1.0, v84, 1.0
	v_fma_f32 v116, -v113, v114, 1.0
	v_fmac_f32_e32 v114, v116, v114
	v_mul_f32_e32 v116, v115, v114
	v_fma_f32 v117, -v113, v116, v115
	v_fmac_f32_e32 v116, v117, v114
	v_fma_f32 v113, -v113, v116, v115
	v_div_fmas_f32 v113, v113, v114, v116
	v_div_fixup_f32 v84, v113, v84, 1.0
.Lp11_ro3:
	s_or_b64 exec, exec, s[4:5]
	v_cmp_ge_u32_e32 vcc, v107, v95
	s_and_saveexec_b64 s[4:5], vcc
	s_cbranch_execz .Lp11_ro4
	v_fmamk_f32 v94, v94, 0x3a800000, v87
	v_mul_f32_e32 v113, 0x4f800000, v94
	v_cmp_gt_f32_e32 vcc, s23, v94
	s_nop 1
	v_cndmask_b32_e32 v94, v94, v113, vcc
	v_sqrt_f32_e32 v113, v94
	s_nop 0
	v_add_u32_e32 v114, -1, v113
	v_add_u32_e32 v115, 1, v113
	v_fma_f32 v116, -v114, v113, v94
	v_fma_f32 v117, -v115, v113, v94
	v_cmp_ge_f32_e64 s[0:1], 0, v116
	s_nop 1
	v_cndmask_b32_e64 v113, v113, v114, s[0:1]
	v_cmp_lt_f32_e64 s[0:1], 0, v117
	s_nop 1
	v_cndmask_b32_e64 v113, v113, v115, s[0:1]
	v_mul_f32_e32 v114, 0x37800000, v113
	v_cndmask_b32_e32 v113, v113, v114, vcc
	v_cmp_class_f32_e32 vcc, v94, v89
	s_nop 1
	v_cndmask_b32_e32 v94, v113, v94, vcc
	v_div_scale_f32 v113, s[0:1], v94, v94, 1.0
	v_rcp_f32_e32 v114, v113
	v_div_scale_f32 v115, vcc, 1.0, v94, 1.0
	v_fma_f32 v116, -v113, v114, 1.0
	v_fmac_f32_e32 v114, v116, v114
	v_mul_f32_e32 v116, v115, v114
	v_fma_f32 v117, -v113, v116, v115
	v_fmac_f32_e32 v116, v117, v114
	v_fma_f32 v113, -v113, v116, v115
	v_div_fmas_f32 v113, v113, v114, v116
	v_div_fixup_f32 v94, v113, v94, 1.0
; __global__ void __launch_bounds__(512) fwd_kernel(Params P) {
;     ...
;                             co[k] = old ? *(const u32x4*)(H16 + (size_t)(row0 + tt - w) * DM + c0) : (u32x4){0u, 0u, 0u, 0u}; ro[k] = old ? 1.f / sqrtf(SSQ[3 * (size_t)MT + row0 + tt - w] * (1.f / DM) + RMS_EPS) : 0.f; }
.Lp11_ro4:
	s_or_b64 exec, exec, s[4:5]
	v_cmp_ge_u32_e32 vcc, v109, v95
	s_and_saveexec_b64 s[4:5], vcc
	s_cbranch_execz .Lp11_ro5
	v_fmamk_f32 v86, v86, 0x3a800000, v87
	v_mul_f32_e32 v113, 0x4f800000, v86
	v_cmp_gt_f32_e32 vcc, s23, v86
	s_nop 1
	v_cndmask_b32_e32 v86, v86, v113, vcc
	v_sqrt_f32_e32 v113, v86
	s_nop 0
	v_add_u32_e32 v114, -1, v113
	v_add_u32_e32 v115, 1, v113
	v_fma_f32 v116, -v114, v113, v86
	v_fma_f32 v117, -v115, v113, v86
	v_cmp_ge_f32_e64 s[0:1], 0, v116
	s_nop 1
	v_cndmask_b32_e64 v113, v113, v114, s[0:1]
	v_cmp_lt_f32_e64 s[0:1], 0, v117
	s_nop 1
	v_cndmask_b32_e64 v113, v113, v115, s[0:1]
	v_mul_f32_e32 v114, 0x37800000, v113
	v_cndmask_b32_e32 v113, v113, v114, vcc
	v_cmp_class_f32_e32 vcc, v86, v89
	s_nop 1
	v_cndmask_b32_e32 v86, v113, v86, vcc
	v_div_scale_f32 v113, s[0:1], v86, v86, 1.0
	v_rcp_f32_e32 v114, v113
	v_div_scale_f32 v115, vcc, 1.0, v86, 1.0
	v_fma_f32 v116, -v113, v114, 1.0
	v_fmac_f32_e32 v114, v116, v114
	v_mul_f32_e32 v116, v115, v114
	v_fma_f32 v117, -v113, v116, v115
	v_fmac_f32_e32 v116, v117, v114
	v_fma_f32 v113, -v113, v116, v115
	v_div_fmas_f32 v113, v113, v114, v116
	v_div_fixup_f32 v86, v113, v86, 1.0
.Lp11_ro5:
	s_or_b64 exec, exec, s[4:5]
	v_cmp_ge_u32_e32 vcc, v110, v95
	s_and_saveexec_b64 s[4:5], vcc
	s_cbranch_execz .Lp11_ro6
	v_fmamk_f32 v96, v96, 0x3a800000, v87
	v_mul_f32_e32 v113, 0x4f800000, v96
	v_cmp_gt_f32_e32 vcc, s23, v96
	s_nop 1
	v_cndmask_b32_e32 v96, v96, v113, vcc
	v_sqrt_f32_e32 v113, v96
	s_nop 0
	v_add_u32_e32 v114, -1, v113
	v_add_u32_e32 v115, 1, v113
	v_fma_f32 v116, -v114, v113, v96
	v_fma_f32 v117, -v115, v113, v96
	v_cmp_ge_f32_e64 s[0:1], 0, v116
	s_nop 1
	v_cndmask_b32_e64 v113, v113, v114, s[0:1]
	v_cmp_lt_f32_e64 s[0:1], 0, v117
	s_nop 1
	v_cndmask_b32_e64 v113, v113, v115, s[0:1]
	v_mul_f32_e32 v114, 0x37800000, v113
	v_cndmask_b32_e32 v113, v113, v114, vcc
	v_cmp_class_f32_e32 vcc, v96, v89
	s_nop 1
	v_cndmask_b32_e32 v96, v113, v96, vcc
	v_div_scale_f32 v113, s[0:1], v96, v96, 1.0
	v_rcp_f32_e32 v114, v113
	v_div_scale_f32 v115, vcc, 1.0, v96, 1.0
	v_fma_f32 v116, -v113, v114, 1.0
	v_fmac_f32_e32 v114, v116, v114
	v_mul_f32_e32 v116, v115, v114
	v_fma_f32 v117, -v113, v116, v115
	v_fmac_f32_e32 v116, v117, v114
	v_fma_f32 v113, -v113, v116, v115
	v_div_fmas_f32 v113, v113, v114, v116
	v_div_fixup_f32 v96, v113, v96, 1.0
.Lp11_ro6:
	s_or_b64 exec, exec, s[4:5]
	v_cmp_ge_u32_e32 vcc, v111, v95
	s_and_saveexec_b64 s[4:5], vcc
	s_cbranch_execz .Lp11_ro7
	v_fmamk_f32 v92, v92, 0x3a800000, v87
	v_mul_f32_e32 v113, 0x4f800000, v92
	v_cmp_gt_f32_e32 vcc, s23, v92
	s_nop 1
	v_cndmask_b32_e32 v92, v92, v113, vcc
	v_sqrt_f32_e32 v113, v92
	s_nop 0
	v_add_u32_e32 v114, -1, v113
	v_add_u32_e32 v115, 1, v113
	v_fma_f32 v116, -v114, v113, v92
	v_fma_f32 v117, -v115, v113, v92
	v_cmp_ge_f32_e64 s[0:1], 0, v116
	s_nop 1
	v_cndmask_b32_e64 v113, v113, v114, s[0:1]
	v_cmp_lt_f32_e64 s[0:1], 0, v117
	s_nop 1
	v_cndmask_b32_e64 v113, v113, v115, s[0:1]
	v_mul_f32_e32 v114, 0x37800000, v113
	v_cndmask_b32_e32 v113, v113, v114, vcc
	v_cmp_class_f32_e32 vcc, v92, v89
	s_nop 1
	v_cndmask_b32_e32 v92, v113, v92, vcc
	v_div_scale_f32 v113, s[0:1], v92, v92, 1.0
	v_rcp_f32_e32 v114, v113
	v_div_scale_f32 v115, vcc, 1.0, v92, 1.0
	v_fma_f32 v116, -v113, v114, 1.0
	v_fmac_f32_e32 v114, v116, v114
	v_mul_f32_e32 v116, v115, v114
	v_fma_f32 v117, -v113, v116, v115
	v_fmac_f32_e32 v116, v117, v114
	v_fma_f32 v113, -v113, v116, v115
	v_div_fmas_f32 v113, v113, v114, v116
	v_div_fixup_f32 v92, v113, v92, 1.0
.Lp11_ro7:
	s_or_b64 exec, exec, s[4:5]
	s_branch .LBB0_1284
